# phase-0 LoRA weight packing: per-thread loads issued together (<=8), one wait, then convert + store, instead of 16 serial load/wait/store iterations
# speedup vs baseline: 1.0022x; 1.0022x over previous
; __device__ __forceinline__ u16 f2bf(float f) { unsigned u = __float_as_uint(f); u += 0x7FFFu + ((u >> 16) & 1u); return (u16)(u >> 16); }
; __device__ __forceinline__ void phase0(const Params& p, unsigned char* lds) {
;     ...
;         u16* Bt = (u16*)(ws + OFF_WB_LORA);
;         for (int idx = gtid; idx < 4096 * 512; idx += nth) { const int n = idx >> 9, k = idx & 511; float v = 0.f;
;             if (n < 2048) { if (k < 96) v = p.rwkv_w_up[((size_t)(n >> 10) * 96 + k) * 1024 + (n & 1023)]; }
;             else if (n < 3072) { if (k >= 96 && k < 192) v = p.rwkv_a_up[(size_t)(k - 96) * 1024 + (n - 2048)]; }
;             else { if (k >= 192 && k < 448) v = p.rwkv_g_up[(size_t)(k - 192) * 1024 + (n - 3072)]; }
;             Bt[idx] = f2bf(v); }
.LBB0_78:
	s_lshl_b32 s69, s68, 9
	v_add_u32_e32 v2, s69, v1
	s_mov_b32 s2, 0x200000
	s_lshl_b32 s40, s33, 9
	v_cmp_gt_i32_e32 vcc, s2, v2
	v_ashrrev_i32_e32 v3, 31, v2
	s_and_saveexec_b64 s[12:13], vcc
	s_cbranch_execz .LBB0_95
	s_load_dwordx16 s[44:59], s[0:1], 0x40
	v_and_b32_e32 v4, 0x1ff, v1
	s_movk_i32 s38, 0x7fff
	s_mov_b32 s39, 0x1fffff
	v_lshl_add_u64 v[12:13], v[2:3], 1, s[90:91]
	s_mov_b64 s[2:3], 0x1a00000
	v_lshl_add_u64 v[12:13], v[12:13], 0, s[2:3]
	s_lshl_b32 s14, s40, 1
	s_mov_b32 s15, 0
	s_lshl_b32 s6, s68, 2
	s_mov_b32 s4, 0x60000
	s_mov_b32 s5, 0
	v_mov_b32_e32 v15, 0
	v_mov_b32_e32 v34, 0
	v_mov_b32_e32 v35, 0
	v_mov_b32_e32 v36, 0
	v_mov_b32_e32 v37, 0
	v_mov_b32_e32 v38, 0
	v_mov_b32_e32 v39, 0
	v_mov_b32_e32 v40, 0
	v_mov_b32_e32 v41, 0
	v_mov_b32_e32 v42, 0
	v_mov_b32_e32 v43, 0
	v_mov_b32_e32 v44, 0
	v_mov_b32_e32 v45, 0
	v_mov_b32_e32 v46, 0
	v_mov_b32_e32 v47, 0
	v_mov_b32_e32 v48, 0
	v_mov_b32_e32 v49, 0
	s_waitcnt lgkmcnt(0)
	v_cmp_gt_u32_e32 vcc, 0x60, v4
	s_and_saveexec_b64 s[16:17], vcc
	s_cbranch_execz .Llora_b
	v_lshlrev_b32_e32 v14, 12, v4
	v_add_u32_e32 v14, s6, v14
	v_lshl_add_u64 v[8:9], s[52:53], 0, v[14:15]
	v_lshl_add_u64 v[10:11], v[8:9], 0, s[4:5]
	global_load_dword v34, v[8:9], off
	global_load_dword v35, v[8:9], off offset:1024
	global_load_dword v36, v[8:9], off offset:2048
	global_load_dword v37, v[8:9], off offset:3072
	global_load_dword v38, v[10:11], off
	global_load_dword v39, v[10:11], off offset:1024
	global_load_dword v40, v[10:11], off offset:2048
	global_load_dword v41, v[10:11], off offset:3072
.Llora_b:
	s_or_b64 exec, exec, s[16:17]
	v_subrev_u32_e32 v7, 0x60, v4
	v_cmp_gt_u32_e32 vcc, 0x60, v7
	s_and_saveexec_b64 s[16:17], vcc
	s_cbranch_execz .Llora_c
	v_lshlrev_b32_e32 v14, 12, v7
	v_add_u32_e32 v14, s6, v14
	v_lshl_add_u64 v[8:9], s[56:57], 0, v[14:15]
	global_load_dword v42, v[8:9], off
	global_load_dword v43, v[8:9], off offset:1024
	global_load_dword v44, v[8:9], off offset:2048
	global_load_dword v45, v[8:9], off offset:3072
.Llora_c:
	s_or_b64 exec, exec, s[16:17]
	v_add_u32_e32 v7, 0xffffff40, v4
	v_cmp_gt_u32_e32 vcc, 0x100, v7
	s_and_saveexec_b64 s[16:17], vcc
	s_cbranch_execz .Llora_d
	v_lshlrev_b32_e32 v14, 12, v7
	v_add_u32_e32 v14, s6, v14
	v_lshl_add_u64 v[8:9], s[58:59], 0, v[14:15]
	global_load_dword v46, v[8:9], off
	global_load_dword v47, v[8:9], off offset:1024
	global_load_dword v48, v[8:9], off offset:2048
	global_load_dword v49, v[8:9], off offset:3072
.Llora_d:
	s_or_b64 exec, exec, s[16:17]
	s_waitcnt vmcnt(0)
	v_bfe_u32 v7, v34, 16, 1
	v_add3_u32 v7, v34, v7, s38
	global_store_short_d16_hi v[12:13], v7, off
	v_lshl_add_u64 v[12:13], v[12:13], 0, s[14:15]
	v_bfe_u32 v7, v35, 16, 1
	v_add3_u32 v7, v35, v7, s38
	global_store_short_d16_hi v[12:13], v7, off
	v_lshl_add_u64 v[12:13], v[12:13], 0, s[14:15]
	v_bfe_u32 v7, v36, 16, 1
	v_add3_u32 v7, v36, v7, s38
	global_store_short_d16_hi v[12:13], v7, off
	v_lshl_add_u64 v[12:13], v[12:13], 0, s[14:15]
	v_bfe_u32 v7, v37, 16, 1
	v_add3_u32 v7, v37, v7, s38
	global_store_short_d16_hi v[12:13], v7, off
	v_lshl_add_u64 v[12:13], v[12:13], 0, s[14:15]
	v_bfe_u32 v7, v38, 16, 1
	v_add3_u32 v7, v38, v7, s38
	global_store_short_d16_hi v[12:13], v7, off
	v_lshl_add_u64 v[12:13], v[12:13], 0, s[14:15]
	v_bfe_u32 v7, v39, 16, 1
	v_add3_u32 v7, v39, v7, s38
	global_store_short_d16_hi v[12:13], v7, off
	v_lshl_add_u64 v[12:13], v[12:13], 0, s[14:15]
	v_bfe_u32 v7, v40, 16, 1
	v_add3_u32 v7, v40, v7, s38
	global_store_short_d16_hi v[12:13], v7, off
	v_lshl_add_u64 v[12:13], v[12:13], 0, s[14:15]
	v_bfe_u32 v7, v41, 16, 1
	v_add3_u32 v7, v41, v7, s38
	global_store_short_d16_hi v[12:13], v7, off
	v_lshl_add_u64 v[12:13], v[12:13], 0, s[14:15]
	v_bfe_u32 v7, v42, 16, 1
	v_add3_u32 v7, v42, v7, s38
	global_store_short_d16_hi v[12:13], v7, off
	v_lshl_add_u64 v[12:13], v[12:13], 0, s[14:15]
	v_bfe_u32 v7, v43, 16, 1
	v_add3_u32 v7, v43, v7, s38
	global_store_short_d16_hi v[12:13], v7, off
	v_lshl_add_u64 v[12:13], v[12:13], 0, s[14:15]
	v_bfe_u32 v7, v44, 16, 1
	v_add3_u32 v7, v44, v7, s38
	global_store_short_d16_hi v[12:13], v7, off
	v_lshl_add_u64 v[12:13], v[12:13], 0, s[14:15]
	v_bfe_u32 v7, v45, 16, 1
	v_add3_u32 v7, v45, v7, s38
	global_store_short_d16_hi v[12:13], v7, off
	v_lshl_add_u64 v[12:13], v[12:13], 0, s[14:15]
	v_bfe_u32 v7, v46, 16, 1
	v_add3_u32 v7, v46, v7, s38
	global_store_short_d16_hi v[12:13], v7, off
	v_lshl_add_u64 v[12:13], v[12:13], 0, s[14:15]
	v_bfe_u32 v7, v47, 16, 1
	v_add3_u32 v7, v47, v7, s38
	global_store_short_d16_hi v[12:13], v7, off
	v_lshl_add_u64 v[12:13], v[12:13], 0, s[14:15]
	v_bfe_u32 v7, v48, 16, 1
	v_add3_u32 v7, v48, v7, s38
	global_store_short_d16_hi v[12:13], v7, off
	v_lshl_add_u64 v[12:13], v[12:13], 0, s[14:15]
	v_bfe_u32 v7, v49, 16, 1
	v_add3_u32 v7, v49, v7, s38
	global_store_short_d16_hi v[12:13], v7, off
